# NSA phase: waves of every other group of 32 workgroups per XCD run at a higher wave priority (asymmetric priority between co-resident workgroups)
# baseline (speedup 1.0000x reference)
; __global__ void __launch_bounds__(256, 2) fwd_mega(Params p) {
;     ...
;         case 3: {
;           if (rep == 0) for (int it = blockIdx.x; it < 512; it += gridDim.x) { if (PHMASK & 8) ssd_carry_item(p, it); }
;           if (xm.ok) {
;             const int bg = xm.xcd >> 1, sub = xm.xcd & 1;
;             for (int k = xm.loc; k < 512; k += xm.nloc) { if (PHMASK & 16) nsa_item(p, bg * 4096 + (2 * k + sub) * 4 + wave, (float*)smem + wave * 3200); }
;           } else {
;             for (int it = blockIdx.x; it < 4096; it += gridDim.x) { if (PHMASK & 16) nsa_item(p, it * 4 + wave, (float*)smem + wave * 3200); }
;           }
.LBB0_327:
	v_readlane_b32 s2, v251, 18
	v_readlane_b32 s3, v251, 19
	s_andn2_b64 vcc, exec, s[2:3]
	s_cbranch_vccnz .LBB0_437
	v_readlane_b32 s2, v251, 20
	v_readlane_b32 s3, v251, 21
	s_andn2_b64 vcc, exec, s[2:3]
	v_readlane_b32 s2, v252, 46
	v_readlane_b32 s3, v252, 44
	s_bitcmp1_b32 s3, 5
	s_cbranch_scc0 .Lnsa_prio_skip
	s_setprio 2
.Lnsa_prio_skip:
	s_cbranch_vccz .LBB0_331
